# build_cum gate-weight loads issued as one burst (dropped xnack-only mid wait); NOSWAP attention; full stack
# baseline (speedup 1.0000x reference)
; __device__ __forceinline__ void build_cum(const Args& a, int L, int hl, long R0, const bf16_t* __restrict__ proj, LAS unsigned char* lds) {
;     ...
;     if (hl < 4) {
;         float gw[16];
; #pragma unroll
;         for (int r = 0; r < 16; ++r) gw[r] = a.gate_w[((size_t)(L * 2 + dir) * 16 + r) * 256 + hl * 64 + k];
;         const float gb = a.gate_b[(L * 2 + dir) * 256 + hl * 64 + k];
.LBB0_121:
	s_ashr_i32 s4, s15, 9
	s_ashr_i32 s5, s4, 31
	s_and_b64 vcc, exec, s[0:1]
	s_cbranch_vccz .LBB0_124
	v_readlane_b32 s0, v254, 43
	s_lshl_b32 s24, s28, 8
	v_readlane_b32 s1, v254, 44
	v_or_b32_e32 v2, s0, v19
	v_ashrrev_i32_e32 v3, 31, v2
	v_lshlrev_b64 v[2:3], 14, v[2:3]
	v_lshl_add_u64 v[2:3], s[48:49], 0, v[2:3]
	v_lshl_add_u64 v[2:3], v[2:3], 0, s[24:25]
	v_lshl_add_u64 v[26:27], v[2:3], 0, v[0:1]
	v_add_co_u32_e32 v16, vcc, s94, v26
	s_lshl_b32 s0, s28, 6
	s_nop 0
	v_addc_co_u32_e32 v17, vcc, 0, v27, vcc
	v_add_co_u32_e32 v28, vcc, s17, v26
	global_load_dword v2, v[26:27], off
	global_load_dword v4, v[26:27], off offset:1024
	global_load_dword v6, v[26:27], off offset:2048
	global_load_dword v8, v[26:27], off offset:3072
	global_load_dword v10, v[16:17], off
	global_load_dword v12, v[16:17], off offset:1024
	global_load_dword v14, v[16:17], off offset:2048
	s_nop 0
	global_load_dword v16, v[16:17], off offset:3072
	v_addc_co_u32_e32 v29, vcc, 0, v27, vcc
	v_add_co_u32_e32 v26, vcc, s59, v26
	v_lshl_or_b32 v22, v19, 8, s1
	s_nop 0
	v_addc_co_u32_e32 v27, vcc, 0, v27, vcc
	global_load_dword v3, v[28:29], off
	global_load_dword v5, v[28:29], off offset:1024
	global_load_dword v7, v[28:29], off offset:2048
	global_load_dword v9, v[28:29], off offset:3072
	global_load_dword v11, v[26:27], off
	global_load_dword v13, v[26:27], off offset:1024
	global_load_dword v15, v[26:27], off offset:2048
	global_load_dword v17, v[26:27], off offset:3072
	v_or3_b32 v26, v22, s0, v21
	v_ashrrev_i32_e32 v27, 31, v26
	v_lshl_add_u64 v[26:27], v[26:27], 2, s[66:67]
	global_load_dword v22, v[26:27], off
	s_and_b32 s0, s14, 63
	s_mul_i32 s0, s0, 0xc8000
	s_mul_i32 s10, s4, 0x3200000
	s_mul_hi_i32 s1, s4, 0x3200000
	s_add_u32 s0, s10, s0
	s_addc_u32 s1, s1, 0
	v_lshl_add_u32 v19, v19, 14, v23
	v_mov_b64_e32 v[26:27], s[0:1]
	v_or_b32_e32 v0, v19, v0
	v_mad_i64_i32 v[18:19], s[0:1], v18, s79, v[26:27]
	v_lshrrev_b32_e32 v23, 1, v20
	v_and_or_b32 v18, v23, 32, v18
	v_add_u32_e32 v0, 0, v0
	v_lshl_add_u64 v[18:19], s[98:99], 0, v[18:19]
	s_mov_b64 s[10:11], 0

; __device__ __forceinline__ void build_cum(const Args& a, int L, int hl, long R0, const bf16_t* __restrict__ proj, LAS unsigned char* lds) {
;     ...
;     if (hl < 4) {
;         float gw[16];
; #pragma unroll
;         for (int r = 0; r < 16; ++r) gw[r] = a.gate_w[((size_t)(L * 2 + dir) * 16 + r) * 256 + hl * 64 + k];
;         const float gb = a.gate_b[(L * 2 + dir) * 256 + hl * 64 + k];
.LBB0_162:
	s_ashr_i32 s4, s13, 9
	s_ashr_i32 s5, s4, 31
	s_and_b64 vcc, exec, s[0:1]
	s_cbranch_vccz .LBB0_165
	v_readlane_b32 s0, v254, 43
	s_lshl_b32 s24, s14, 8
	v_readlane_b32 s1, v254, 44
	v_or_b32_e32 v2, s0, v19
	v_ashrrev_i32_e32 v3, 31, v2
	v_lshlrev_b64 v[2:3], 14, v[2:3]
	v_lshl_add_u64 v[2:3], s[48:49], 0, v[2:3]
	v_lshl_add_u64 v[2:3], v[2:3], 0, s[24:25]
	v_lshl_add_u64 v[24:25], v[2:3], 0, v[0:1]
	v_add_co_u32_e32 v16, vcc, s94, v24
	s_lshl_b32 s0, s14, 6
	s_nop 0
	v_addc_co_u32_e32 v17, vcc, 0, v25, vcc
	v_add_co_u32_e32 v26, vcc, s17, v24
	global_load_dword v2, v[24:25], off
	global_load_dword v4, v[24:25], off offset:1024
	global_load_dword v6, v[24:25], off offset:2048
	global_load_dword v8, v[24:25], off offset:3072
	global_load_dword v10, v[16:17], off
	global_load_dword v12, v[16:17], off offset:1024
	global_load_dword v14, v[16:17], off offset:2048
	s_nop 0
	global_load_dword v16, v[16:17], off offset:3072
	v_addc_co_u32_e32 v27, vcc, 0, v25, vcc
	v_add_co_u32_e32 v24, vcc, s59, v24
	v_lshl_or_b32 v22, v19, 8, s1
	s_nop 0
	v_addc_co_u32_e32 v25, vcc, 0, v25, vcc
	global_load_dword v3, v[26:27], off
	global_load_dword v5, v[26:27], off offset:1024
	global_load_dword v7, v[26:27], off offset:2048
	global_load_dword v9, v[26:27], off offset:3072
	global_load_dword v11, v[24:25], off
	global_load_dword v13, v[24:25], off offset:1024
	global_load_dword v15, v[24:25], off offset:2048
	global_load_dword v17, v[24:25], off offset:3072
	v_or3_b32 v24, v22, s0, v21
	v_ashrrev_i32_e32 v25, 31, v24
	v_lshl_add_u64 v[24:25], v[24:25], 2, s[66:67]
	global_load_dword v22, v[24:25], off
	s_and_b32 s0, s12, 63
	s_mul_i32 s0, s0, 0xc8000
	s_mul_i32 s10, s4, 0x3200000
	s_mul_hi_i32 s1, s4, 0x3200000
	s_add_u32 s0, s10, s0
	s_addc_u32 s1, s1, 0
	v_lshl_add_u32 v19, v19, 14, v23
	v_mov_b64_e32 v[24:25], s[0:1]
	v_or_b32_e32 v0, v19, v0
	v_mad_i64_i32 v[18:19], s[0:1], v18, s79, v[24:25]
	v_lshrrev_b32_e32 v23, 1, v20
	v_and_or_b32 v18, v23, 32, v18
	v_add_u32_e32 v0, 0, v0
	v_lshl_add_u64 v[18:19], s[98:99], 0, v[18:19]
	s_mov_b64 s[10:11], 0
